# swpk: SwiGLU epilogue plain f32 multiplies/adds as v_pk_mul_f32/v_pk_add_f32 (instruction selection)
# baseline (speedup 1.0000x reference)
; #define PG8_STAGE(bufoff, gbase, voff) do { _Pragma("unroll") for (int _i = 0; _i < 2; ++_i) \
;         __builtin_amdgcn_global_load_lds((const unsigned*)((const char*)(gbase) + (voff)[_i]), (PG8_LAS unsigned*)(lds + (bufoff) + ldsw + _i * 8192), 16, 0, 0); } while (0)
; #define PG8_LDA(dst, b, h) do { _Pragma("unroll") for (int m = 0; m < 4; ++m) _Pragma("unroll") for (int k = 0; k < 2; ++k) dst[m][k] = *(const PG8_LAS bf16x8*)(lds + PG8_SA(b, h) + aoff + m * 2048 + k * 1024); } while (0)
; #define PG8_LDB(dst, b, h) do { _Pragma("unroll") for (int n = 0; n < 2; ++n) _Pragma("unroll") for (int k = 0; k < 2; ++k) dst[n][k] = *(const PG8_LAS bf16x8*)(lds + PG8_SB(b, h) + boff + n * 2048 + k * 1024); } while (0)
; #define PG8_MMA(ai, bj, At, Bt) do { __builtin_amdgcn_s_setprio(1); _Pragma("unroll") for (int m = 0; m < 4; ++m) _Pragma("unroll") for (int n = 0; n < 2; ++n) _Pragma("unroll") for (int k = 0; k < 2; ++k) \
;         acc[ai][bj][m][n] = __builtin_amdgcn_mfma_f32_16x16x32_bf16(Bt[n][k], At[m][k], acc[ai][bj][m][n], 0, 0, 0); __builtin_amdgcn_s_setprio(0); } while (0)
; #define PG8_WAIT_V(n) asm volatile("s_waitcnt vmcnt(" #n ")" ::: "memory")
; #define PG8_WAIT_L(n) asm volatile("s_waitcnt lgkmcnt(" #n ")" ::: "memory")
; template <class Epi>
; __device__ __forceinline__ void gemm_phase(PG8_LAS unsigned char* lds, const Gemm g, const Sched& S, const Epi& E) {
;     ...
;         for (int t = 0; t < nt; t += 2) {
;             const bool last = (t == nt - 2);
;             const char* a1 = cA + (size_t)(t + 1) * kstep;
;             const char* a2 = last ? nA : cA + (size_t)(t + 2) * kstep; const char* b2 = last ? nB : cB + (size_t)(t + 2) * kstep;
;             const char* a3 = a2 + kstep; const char* b3 = b2 + kstep;
;             PG8_LDB(B0, 0, 0); PG8_SCHED; PG8_LDA(At, 0, 0); PG8_STAGE(PG8_SA(1, 1), a1 + hsA, voffA);
;             PG8_WAIT_L(8); PG8_BAR; PG8_WAIT_L(0); PG8_MMA(0, 0, At, B0); PG8_BAR; PG8_SCHED;
;             PG8_LDB(B1, 0, 1); PG8_STAGE(PG8_SB(0, 0), b2, voffB);
;             PG8_BAR; PG8_WAIT_L(0); PG8_MMA(0, 1, At, B1); PG8_BAR;
;             PG8_LDA(At, 0, 1); PG8_STAGE(PG8_SA(0, 0), a2, voffA);
;             PG8_BAR; PG8_WAIT_L(0); PG8_MMA(1, 0, At, B0); PG8_BAR; PG8_SCHED;
;             PG8_STAGE(PG8_SB(0, 1), b2 + hsB, voffB);
;             PG8_WAIT_V(6); PG8_BAR; PG8_MMA(1, 1, At, B1); PG8_BAR;
.LBB0_908:
	s_add_u32 s8, s6, 0xfffc0080
	s_addc_u32 s9, s7, -1
	s_add_i32 s56, 0, 0x10000
	v_add_u32_e32 v145, s56, v135
	ds_read_b128 v[146:149], v145
	ds_read_b128 v[150:153], v145 offset:1024
	ds_read_b128 v[154:157], v145 offset:2048
	ds_read_b128 v[158:161], v145 offset:3072
	s_cmp_eq_u32 s55, 12
	s_cselect_b32 s11, s2, s9
	s_cselect_b32 s10, s3, s8
	s_cselect_b32 s9, s36, s49
	s_cselect_b32 s8, s37, s47
	v_lshl_add_u64 v[162:163], s[6:7], 0, v[130:131]
	s_add_i32 m0, s5, 0xc000
	ds_read_b128 v[178:181], v144
	ds_read_b128 v[182:185], v144 offset:1024
	ds_read_b128 v[186:189], v144 offset:2048
	ds_read_b128 v[190:193], v144 offset:3072
	ds_read_b128 v[194:197], v144 offset:4096
	ds_read_b128 v[198:201], v144 offset:5120
	ds_read_b128 v[202:205], v144 offset:6144
	ds_read_b128 v[206:209], v144 offset:7168
	global_load_lds_dwordx4 v[162:163], off
	v_lshl_add_u64 v[162:163], s[6:7], 0, v[132:133]
	s_add_i32 m0, s5, 0xe000
	s_nop 0
	global_load_lds_dwordx4 v[162:163], off
	s_waitcnt lgkmcnt(8)
	s_barrier
	s_waitcnt lgkmcnt(0)
	s_setprio 1
	s_waitcnt lgkmcnt(0)
	v_mfma_f32_16x16x32_bf16 v[124:127], v[146:149], v[178:181], v[124:127]
	v_mfma_f32_16x16x32_bf16 v[120:123], v[154:157], v[178:181], v[120:123]
	v_mfma_f32_16x16x32_bf16 v[108:111], v[146:149], v[186:189], v[108:111]
	v_mfma_f32_16x16x32_bf16 v[104:107], v[154:157], v[186:189], v[104:107]
	v_mfma_f32_16x16x32_bf16 v[92:95], v[146:149], v[194:197], v[92:95]
	v_mfma_f32_16x16x32_bf16 v[88:91], v[154:157], v[194:197], v[88:91]
	v_mfma_f32_16x16x32_bf16 v[76:79], v[146:149], v[202:205], v[76:79]
	v_mfma_f32_16x16x32_bf16 v[72:75], v[154:157], v[202:205], v[72:75]
	v_mfma_f32_16x16x32_bf16 v[124:127], v[150:153], v[182:185], v[124:127]
	v_mfma_f32_16x16x32_bf16 v[120:123], v[158:161], v[182:185], v[120:123]
	v_mfma_f32_16x16x32_bf16 v[108:111], v[150:153], v[190:193], v[108:111]
	v_mfma_f32_16x16x32_bf16 v[104:107], v[158:161], v[190:193], v[104:107]
	v_mfma_f32_16x16x32_bf16 v[92:95], v[150:153], v[198:201], v[92:95]
	v_mfma_f32_16x16x32_bf16 v[88:91], v[158:161], v[198:201], v[88:91]
	v_mfma_f32_16x16x32_bf16 v[76:79], v[150:153], v[206:209], v[76:79]
	v_mfma_f32_16x16x32_bf16 v[72:75], v[158:161], v[206:209], v[72:75]
	s_setprio 0
	s_barrier
	s_add_i32 s58, 0, 0x14000
	s_add_i32 s56, s56, s25
	v_add_u32_e32 v145, s58, v135
	v_lshl_add_u64 v[162:163], s[8:9], 0, v[166:167]
	s_mov_b32 m0, s56
	ds_read_b128 v[210:213], v145
	ds_read_b128 v[236:239], v145 offset:1024
	ds_read_b128 v[240:243], v145 offset:2048
	ds_read_b128 v[244:247], v145 offset:3072
	global_load_lds_dwordx4 v[162:163], off
	v_lshl_add_u64 v[172:173], s[8:9], 0, v[128:129]
	s_add_i32 m0, s56, 0x2000
	s_nop 0
	global_load_lds_dwordx4 v[172:173], off
	s_barrier
	s_waitcnt lgkmcnt(0)
	s_setprio 1
	s_waitcnt lgkmcnt(0)
	v_mfma_f32_16x16x32_bf16 v[116:119], v[210:213], v[178:181], v[116:119]
	v_mfma_f32_16x16x32_bf16 v[112:115], v[240:243], v[178:181], v[112:115]
	v_mfma_f32_16x16x32_bf16 v[100:103], v[210:213], v[186:189], v[100:103]
	v_mfma_f32_16x16x32_bf16 v[96:99], v[240:243], v[186:189], v[96:99]
	v_mfma_f32_16x16x32_bf16 v[84:87], v[210:213], v[194:197], v[84:87]
	v_mfma_f32_16x16x32_bf16 v[80:83], v[240:243], v[194:197], v[80:83]
	v_mfma_f32_16x16x32_bf16 v[68:71], v[210:213], v[202:205], v[68:71]
	v_mfma_f32_16x16x32_bf16 v[64:67], v[240:243], v[202:205], v[64:67]
	v_mfma_f32_16x16x32_bf16 v[116:119], v[236:239], v[182:185], v[116:119]
	v_mfma_f32_16x16x32_bf16 v[112:115], v[244:247], v[182:185], v[112:115]
	v_mfma_f32_16x16x32_bf16 v[100:103], v[236:239], v[190:193], v[100:103]
	v_mfma_f32_16x16x32_bf16 v[96:99], v[244:247], v[190:193], v[96:99]
	v_mfma_f32_16x16x32_bf16 v[84:87], v[236:239], v[198:201], v[84:87]
	v_mfma_f32_16x16x32_bf16 v[80:83], v[244:247], v[198:201], v[80:83]
	v_mfma_f32_16x16x32_bf16 v[68:71], v[236:239], v[206:209], v[68:71]
	v_mfma_f32_16x16x32_bf16 v[64:67], v[244:247], v[206:209], v[64:67]
	s_setprio 0
	s_mov_b32 m0, s5
	v_lshl_add_u64 v[174:175], s[10:11], 0, v[166:167]
	s_barrier
	ds_read_b128 v[178:181], v144 offset:16384
	ds_read_b128 v[182:185], v144 offset:17408
	ds_read_b128 v[186:189], v144 offset:18432
	ds_read_b128 v[190:193], v144 offset:19456
	ds_read_b128 v[194:197], v144 offset:20480
	ds_read_b128 v[198:201], v144 offset:21504
	ds_read_b128 v[202:205], v144 offset:22528
	ds_read_b128 v[206:209], v144 offset:23552
	global_load_lds_dwordx4 v[174:175], off
	v_lshl_add_u64 v[214:215], s[10:11], 0, v[128:129]
	s_mov_b32 m0, s26
	s_nop 0
	global_load_lds_dwordx4 v[214:215], off
	s_barrier
	s_waitcnt lgkmcnt(0)
	s_setprio 1
	s_waitcnt lgkmcnt(0)
	v_mfma_f32_16x16x32_bf16 v[60:63], v[146:149], v[178:181], v[60:63]
	v_mfma_f32_16x16x32_bf16 v[56:59], v[154:157], v[178:181], v[56:59]
	v_mfma_f32_16x16x32_bf16 v[44:47], v[146:149], v[186:189], v[44:47]
	v_mfma_f32_16x16x32_bf16 v[40:43], v[154:157], v[186:189], v[40:43]
	v_mfma_f32_16x16x32_bf16 v[28:31], v[146:149], v[194:197], v[28:31]
	v_mfma_f32_16x16x32_bf16 v[24:27], v[154:157], v[194:197], v[24:27]
	v_mfma_f32_16x16x32_bf16 v[12:15], v[146:149], v[202:205], v[12:15]
	v_mfma_f32_16x16x32_bf16 v[8:11], v[154:157], v[202:205], v[8:11]
	v_mfma_f32_16x16x32_bf16 v[60:63], v[150:153], v[182:185], v[60:63]
	v_mfma_f32_16x16x32_bf16 v[56:59], v[158:161], v[182:185], v[56:59]
	v_mfma_f32_16x16x32_bf16 v[44:47], v[150:153], v[190:193], v[44:47]
	v_mfma_f32_16x16x32_bf16 v[40:43], v[158:161], v[190:193], v[40:43]
	v_mfma_f32_16x16x32_bf16 v[28:31], v[150:153], v[198:201], v[28:31]
	v_mfma_f32_16x16x32_bf16 v[24:27], v[158:161], v[198:201], v[24:27]
	v_mfma_f32_16x16x32_bf16 v[12:15], v[150:153], v[206:209], v[12:15]
	v_mfma_f32_16x16x32_bf16 v[8:11], v[158:161], v[206:209], v[8:11]
	s_setprio 0
	s_barrier
; #define PG8_STAGE(bufoff, gbase, voff) do { _Pragma("unroll") for (int _i = 0; _i < 2; ++_i) \
;         __builtin_amdgcn_global_load_lds((const unsigned*)((const char*)(gbase) + (voff)[_i]), (PG8_LAS unsigned*)(lds + (bufoff) + ldsw + _i * 8192), 16, 0, 0); } while (0)
; #define PG8_LDA(dst, b, h) do { _Pragma("unroll") for (int m = 0; m < 4; ++m) _Pragma("unroll") for (int k = 0; k < 2; ++k) dst[m][k] = *(const PG8_LAS bf16x8*)(lds + PG8_SA(b, h) + aoff + m * 2048 + k * 1024); } while (0)
; #define PG8_LDB(dst, b, h) do { _Pragma("unroll") for (int n = 0; n < 2; ++n) _Pragma("unroll") for (int k = 0; k < 2; ++k) dst[n][k] = *(const PG8_LAS bf16x8*)(lds + PG8_SB(b, h) + boff + n * 2048 + k * 1024); } while (0)
; #define PG8_MMA(ai, bj, At, Bt) do { __builtin_amdgcn_s_setprio(1); _Pragma("unroll") for (int m = 0; m < 4; ++m) _Pragma("unroll") for (int n = 0; n < 2; ++n) _Pragma("unroll") for (int k = 0; k < 2; ++k) \
;         acc[ai][bj][m][n] = __builtin_amdgcn_mfma_f32_16x16x32_bf16(Bt[n][k], At[m][k], acc[ai][bj][m][n], 0, 0, 0); __builtin_amdgcn_s_setprio(0); } while (0)
; #define PG8_WAIT_V(n) asm volatile("s_waitcnt vmcnt(" #n ")" ::: "memory")
; #define PG8_WAIT_L(n) asm volatile("s_waitcnt lgkmcnt(" #n ")" ::: "memory")
; #define PG8_BAR __builtin_amdgcn_s_barrier()
; #define PG8_SCHED __builtin_amdgcn_sched_barrier(0)
; template <class Epi>
; __device__ __forceinline__ void gemm_phase(PG8_LAS unsigned char* lds, const Gemm g, const Sched& S, const Epi& E) {
;     ...
;             PG8_BAR; PG8_WAIT_L(0); PG8_MMA(1, 0, At, B0); PG8_BAR; PG8_SCHED;
;             PG8_STAGE(PG8_SB(0, 1), b2 + hsB, voffB);
;             PG8_WAIT_V(6); PG8_BAR; PG8_MMA(1, 1, At, B1); PG8_BAR;
;             PG8_LDB(B0, 1, 0); PG8_SCHED; PG8_LDA(At, 1, 0); PG8_STAGE(PG8_SA(0, 1), a2 + hsA, voffA);
;             PG8_WAIT_L(8); PG8_BAR; PG8_WAIT_L(0); PG8_MMA(0, 0, At, B0); PG8_BAR; PG8_SCHED;
;             PG8_LDB(B1, 1, 1); PG8_STAGE(PG8_SB(1, 0), b3, voffB);
;             PG8_BAR; PG8_WAIT_L(0); PG8_MMA(0, 1, At, B1); PG8_BAR;
;             PG8_LDA(At, 1, 1); PG8_STAGE(PG8_SA(1, 0), a3, voffA);
;             PG8_BAR; PG8_WAIT_L(0); PG8_MMA(1, 0, At, B0); PG8_BAR; PG8_SCHED;
	s_add_u32 s56, s8, 0x40000
	s_addc_u32 s57, s9, 0
	s_add_i32 s58, s58, s25
	v_lshl_add_u64 v[146:147], s[56:57], 0, v[166:167]
	s_mov_b32 m0, s58
	s_nop 0
	global_load_lds_dwordx4 v[146:147], off
	v_lshl_add_u64 v[146:147], s[56:57], 0, v[128:129]
	s_add_i32 m0, s58, 0x2000
	s_nop 0
	global_load_lds_dwordx4 v[146:147], off
	s_waitcnt vmcnt(6)
	s_barrier
	s_setprio 1
	v_mfma_f32_16x16x32_bf16 v[52:55], v[210:213], v[178:181], v[52:55]
	v_mfma_f32_16x16x32_bf16 v[48:51], v[240:243], v[178:181], v[48:51]
	v_mfma_f32_16x16x32_bf16 v[36:39], v[210:213], v[186:189], v[36:39]
	v_mfma_f32_16x16x32_bf16 v[32:35], v[240:243], v[186:189], v[32:35]
	v_mfma_f32_16x16x32_bf16 v[20:23], v[210:213], v[194:197], v[20:23]
	v_mfma_f32_16x16x32_bf16 v[16:19], v[240:243], v[194:197], v[16:19]
	v_mfma_f32_16x16x32_bf16 v[4:7], v[210:213], v[202:205], v[4:7]
	v_mfma_f32_16x16x32_bf16 v[0:3], v[240:243], v[202:205], v[0:3]
	v_mfma_f32_16x16x32_bf16 v[52:55], v[236:239], v[182:185], v[52:55]
	v_mfma_f32_16x16x32_bf16 v[48:51], v[244:247], v[182:185], v[48:51]
	v_mfma_f32_16x16x32_bf16 v[36:39], v[236:239], v[190:193], v[36:39]
	v_mfma_f32_16x16x32_bf16 v[32:35], v[244:247], v[190:193], v[32:35]
	v_mfma_f32_16x16x32_bf16 v[20:23], v[236:239], v[198:201], v[20:23]
	v_mfma_f32_16x16x32_bf16 v[16:19], v[244:247], v[198:201], v[16:19]
	v_mfma_f32_16x16x32_bf16 v[4:7], v[236:239], v[206:209], v[4:7]
	v_mfma_f32_16x16x32_bf16 v[0:3], v[244:247], v[206:209], v[0:3]
	s_setprio 0
	s_add_i32 s56, 0, 0x18000
	v_add_u32_e32 v145, s56, v135
	s_barrier
	ds_read_b128 v[146:149], v145
	ds_read_b128 v[150:153], v145 offset:1024
	ds_read_b128 v[154:157], v145 offset:2048
	ds_read_b128 v[158:161], v145 offset:3072
	s_add_u32 s10, s10, 0x40000
	s_addc_u32 s11, s11, 0
	s_mov_b32 m0, s27
	v_lshl_add_u64 v[210:211], s[10:11], 0, v[166:167]
	ds_read_b128 v[178:181], v144 offset:32768
	ds_read_b128 v[182:185], v144 offset:33792
	ds_read_b128 v[186:189], v144 offset:34816
	ds_read_b128 v[190:193], v144 offset:35840
	ds_read_b128 v[194:197], v144 offset:36864
	ds_read_b128 v[198:201], v144 offset:37888
	ds_read_b128 v[202:205], v144 offset:38912
	ds_read_b128 v[206:209], v144 offset:39936
	global_load_lds_dwordx4 v[210:211], off
	v_lshl_add_u64 v[210:211], s[10:11], 0, v[128:129]
	s_mov_b32 m0, s38
	s_nop 0
	global_load_lds_dwordx4 v[210:211], off
	s_waitcnt lgkmcnt(8)
	s_barrier
	s_waitcnt lgkmcnt(0)
	s_setprio 1
	s_waitcnt lgkmcnt(0)
	v_mfma_f32_16x16x32_bf16 v[124:127], v[146:149], v[178:181], v[124:127]
	v_mfma_f32_16x16x32_bf16 v[120:123], v[154:157], v[178:181], v[120:123]
	v_mfma_f32_16x16x32_bf16 v[108:111], v[146:149], v[186:189], v[108:111]
	v_mfma_f32_16x16x32_bf16 v[104:107], v[154:157], v[186:189], v[104:107]
	v_mfma_f32_16x16x32_bf16 v[92:95], v[146:149], v[194:197], v[92:95]
	v_mfma_f32_16x16x32_bf16 v[88:91], v[154:157], v[194:197], v[88:91]
	v_mfma_f32_16x16x32_bf16 v[76:79], v[146:149], v[202:205], v[76:79]
	v_mfma_f32_16x16x32_bf16 v[72:75], v[154:157], v[202:205], v[72:75]
	v_mfma_f32_16x16x32_bf16 v[124:127], v[150:153], v[182:185], v[124:127]
	v_mfma_f32_16x16x32_bf16 v[120:123], v[158:161], v[182:185], v[120:123]
	v_mfma_f32_16x16x32_bf16 v[108:111], v[150:153], v[190:193], v[108:111]
	v_mfma_f32_16x16x32_bf16 v[104:107], v[158:161], v[190:193], v[104:107]
	v_mfma_f32_16x16x32_bf16 v[92:95], v[150:153], v[198:201], v[92:95]
	v_mfma_f32_16x16x32_bf16 v[88:91], v[158:161], v[198:201], v[88:91]
	v_mfma_f32_16x16x32_bf16 v[76:79], v[150:153], v[206:209], v[76:79]
	v_mfma_f32_16x16x32_bf16 v[72:75], v[158:161], v[206:209], v[72:75]
	s_setprio 0
	s_barrier
	s_add_i32 s10, 0, 0x1c000
	s_add_i32 s11, s56, s25
	v_add_u32_e32 v145, s10, v135
	v_lshl_add_u64 v[162:163], v[162:163], 0, s[76:77]
	s_mov_b32 m0, s11
	ds_read_b128 v[210:213], v145
	ds_read_b128 v[236:239], v145 offset:1024
	ds_read_b128 v[240:243], v145 offset:2048
	ds_read_b128 v[244:247], v145 offset:3072
	global_load_lds_dwordx4 v[162:163], off
	v_lshl_add_u64 v[162:163], v[172:173], 0, s[76:77]
	s_add_i32 m0, s11, 0x2000
	s_nop 0
	global_load_lds_dwordx4 v[162:163], off
	s_barrier
	s_waitcnt lgkmcnt(0)
	s_setprio 1
	s_waitcnt lgkmcnt(0)
	v_mfma_f32_16x16x32_bf16 v[116:119], v[210:213], v[178:181], v[116:119]
	v_mfma_f32_16x16x32_bf16 v[112:115], v[240:243], v[178:181], v[112:115]
	v_mfma_f32_16x16x32_bf16 v[100:103], v[210:213], v[186:189], v[100:103]
	v_mfma_f32_16x16x32_bf16 v[96:99], v[240:243], v[186:189], v[96:99]
	v_mfma_f32_16x16x32_bf16 v[84:87], v[210:213], v[194:197], v[84:87]
	v_mfma_f32_16x16x32_bf16 v[80:83], v[240:243], v[194:197], v[80:83]
	v_mfma_f32_16x16x32_bf16 v[68:71], v[210:213], v[202:205], v[68:71]
	v_mfma_f32_16x16x32_bf16 v[64:67], v[240:243], v[202:205], v[64:67]
	v_mfma_f32_16x16x32_bf16 v[116:119], v[236:239], v[182:185], v[116:119]
	v_mfma_f32_16x16x32_bf16 v[112:115], v[244:247], v[182:185], v[112:115]
	v_mfma_f32_16x16x32_bf16 v[100:103], v[236:239], v[190:193], v[100:103]
	v_mfma_f32_16x16x32_bf16 v[96:99], v[244:247], v[190:193], v[96:99]
	v_mfma_f32_16x16x32_bf16 v[84:87], v[236:239], v[198:201], v[84:87]
	v_mfma_f32_16x16x32_bf16 v[80:83], v[244:247], v[198:201], v[80:83]
	v_mfma_f32_16x16x32_bf16 v[68:71], v[236:239], v[206:209], v[68:71]
	v_mfma_f32_16x16x32_bf16 v[64:67], v[244:247], v[206:209], v[64:67]
	s_setprio 0
	s_mov_b32 m0, s39
	v_lshl_add_u64 v[162:163], v[174:175], 0, s[76:77]
	s_barrier
	ds_read_b128 v[178:181], v144 offset:49152
	ds_read_b128 v[182:185], v144 offset:50176
	ds_read_b128 v[186:189], v144 offset:51200
	ds_read_b128 v[190:193], v144 offset:52224
	ds_read_b128 v[194:197], v144 offset:53248
	ds_read_b128 v[198:201], v144 offset:54272
	ds_read_b128 v[202:205], v144 offset:55296
	ds_read_b128 v[206:209], v144 offset:56320
	global_load_lds_dwordx4 v[162:163], off
	v_lshl_add_u64 v[162:163], v[214:215], 0, s[76:77]
	s_mov_b32 m0, s54
	s_nop 0
	global_load_lds_dwordx4 v[162:163], off
	s_barrier
; __device__ __forceinline__ uint32_t pack2(float a, float b) { uint32_t r; asm("v_cvt_pk_bf16_f32 %0, %1, %2" : "=v"(r) : "v"(a), "v"(b)); return r; }
; __device__ __forceinline__ float siluf_(float x) { return x * __builtin_amdgcn_rcpf(1.0f + __expf(-x)); }
; #define PG8_STAGE(bufoff, gbase, voff) do { _Pragma("unroll") for (int _i = 0; _i < 2; ++_i) \
;         __builtin_amdgcn_global_load_lds((const unsigned*)((const char*)(gbase) + (voff)[_i]), (PG8_LAS unsigned*)(lds + (bufoff) + ldsw + _i * 8192), 16, 0, 0); } while (0)
; #define PG8_LDA(dst, b, h) do { _Pragma("unroll") for (int m = 0; m < 4; ++m) _Pragma("unroll") for (int k = 0; k < 2; ++k) dst[m][k] = *(const PG8_LAS bf16x8*)(lds + PG8_SA(b, h) + aoff + m * 2048 + k * 1024); } while (0)
; #define PG8_LDB(dst, b, h) do { _Pragma("unroll") for (int n = 0; n < 2; ++n) _Pragma("unroll") for (int k = 0; k < 2; ++k) dst[n][k] = *(const PG8_LAS bf16x8*)(lds + PG8_SB(b, h) + boff + n * 2048 + k * 1024); } while (0)
; #define PG8_BAR __builtin_amdgcn_s_barrier()
; template <class Epi>
; __device__ __forceinline__ void gemm_phase(PG8_LAS unsigned char* lds, const Gemm g, const Sched& S, const Epi& E) {
;     ...
;             PG8_LDB(B0, 1, 0); PG8_SCHED; PG8_LDA(At, 1, 0); PG8_STAGE(PG8_SA(0, 1), a2 + hsA, voffA);
;             PG8_WAIT_L(8); PG8_BAR; PG8_WAIT_L(0); PG8_MMA(0, 0, At, B0); PG8_BAR; PG8_SCHED;
;             PG8_LDB(B1, 1, 1); PG8_STAGE(PG8_SB(1, 0), b3, voffB);
;             PG8_BAR; PG8_WAIT_L(0); PG8_MMA(0, 1, At, B1); PG8_BAR;
;             PG8_LDA(At, 1, 1); PG8_STAGE(PG8_SA(1, 0), a3, voffA);
;             PG8_BAR; PG8_WAIT_L(0); PG8_MMA(1, 0, At, B0); PG8_BAR; PG8_SCHED;
;             PG8_STAGE(PG8_SB(1, 1), b3 + hsB, voffB);
;             PG8_WAIT_V(6); PG8_BAR; PG8_MMA(1, 1, At, B1); PG8_BAR;
;         }
;   __device__ __forceinline__ void operator()(const f32x4 (&acc)[2][2][4][2], const pg8::Unit& u, int wr, int wc, int fr, int fq) const {
;     ...
;         if (kind == EPI_SWIGLU) {
; #pragma unroll
;           for (int bj = 0; bj < 2; ++bj) {
;             int hc = u.pn * 128 + bj * 64 + wc * 16 + fq * 4;
;             f32x4 g = acc[ai][bj][m][0], up = acc[ai][bj][m][1];
;             uint2 o; o.x = pack2(siluf_(g[0]) * up[0], siluf_(g[1]) * up[1]); o.y = pack2(siluf_(g[2]) * up[2], siluf_(g[3]) * up[3]);
;             *(uint2*)(outb + (size_t)row * ldo + hc) = o;
;           }
	s_waitcnt lgkmcnt(0)
	s_setprio 1
	s_waitcnt lgkmcnt(0)
	v_mfma_f32_16x16x32_bf16 v[60:63], v[146:149], v[178:181], v[60:63]
	v_mfma_f32_16x16x32_bf16 v[56:59], v[154:157], v[178:181], v[56:59]
	v_mfma_f32_16x16x32_bf16 v[44:47], v[146:149], v[186:189], v[44:47]
	v_mfma_f32_16x16x32_bf16 v[40:43], v[154:157], v[186:189], v[40:43]
	v_mfma_f32_16x16x32_bf16 v[28:31], v[146:149], v[194:197], v[28:31]
	v_mfma_f32_16x16x32_bf16 v[24:27], v[154:157], v[194:197], v[24:27]
	v_mfma_f32_16x16x32_bf16 v[12:15], v[146:149], v[202:205], v[12:15]
	v_mfma_f32_16x16x32_bf16 v[8:11], v[154:157], v[202:205], v[8:11]
	v_mfma_f32_16x16x32_bf16 v[60:63], v[150:153], v[182:185], v[60:63]
	v_mfma_f32_16x16x32_bf16 v[56:59], v[158:161], v[182:185], v[56:59]
	v_mfma_f32_16x16x32_bf16 v[44:47], v[150:153], v[190:193], v[44:47]
	v_mfma_f32_16x16x32_bf16 v[40:43], v[158:161], v[190:193], v[40:43]
	v_mfma_f32_16x16x32_bf16 v[28:31], v[150:153], v[198:201], v[28:31]
	v_mfma_f32_16x16x32_bf16 v[24:27], v[158:161], v[198:201], v[24:27]
	v_mfma_f32_16x16x32_bf16 v[12:15], v[150:153], v[206:209], v[12:15]
	v_mfma_f32_16x16x32_bf16 v[8:11], v[158:161], v[206:209], v[8:11]
	s_setprio 0
	s_barrier
	s_add_u32 s8, s8, 0x40080
	s_addc_u32 s9, s9, 0
	s_add_i32 s10, s10, s25
	v_lshl_add_u64 v[146:147], s[8:9], 0, v[166:167]
	s_mov_b32 m0, s10
	s_nop 0
	global_load_lds_dwordx4 v[146:147], off
	v_lshl_add_u64 v[146:147], s[8:9], 0, v[128:129]
	s_add_i32 m0, s10, 0x2000
	s_nop 0
	global_load_lds_dwordx4 v[146:147], off
	s_waitcnt vmcnt(6)
	s_barrier
	s_setprio 1
	v_mfma_f32_16x16x32_bf16 v[52:55], v[210:213], v[178:181], v[52:55]
	v_mfma_f32_16x16x32_bf16 v[48:51], v[240:243], v[178:181], v[48:51]
	v_mfma_f32_16x16x32_bf16 v[36:39], v[210:213], v[186:189], v[36:39]
	v_mfma_f32_16x16x32_bf16 v[32:35], v[240:243], v[186:189], v[32:35]
	v_mfma_f32_16x16x32_bf16 v[20:23], v[210:213], v[194:197], v[20:23]
	v_mfma_f32_16x16x32_bf16 v[16:19], v[240:243], v[194:197], v[16:19]
	v_mfma_f32_16x16x32_bf16 v[4:7], v[210:213], v[202:205], v[4:7]
	v_mfma_f32_16x16x32_bf16 v[0:3], v[240:243], v[202:205], v[0:3]
	v_mfma_f32_16x16x32_bf16 v[52:55], v[236:239], v[182:185], v[52:55]
	v_mfma_f32_16x16x32_bf16 v[48:51], v[244:247], v[182:185], v[48:51]
	v_mfma_f32_16x16x32_bf16 v[36:39], v[236:239], v[190:193], v[36:39]
	v_mfma_f32_16x16x32_bf16 v[32:35], v[244:247], v[190:193], v[32:35]
	v_mfma_f32_16x16x32_bf16 v[20:23], v[236:239], v[198:201], v[20:23]
	v_mfma_f32_16x16x32_bf16 v[16:19], v[244:247], v[198:201], v[16:19]
	v_mfma_f32_16x16x32_bf16 v[4:7], v[236:239], v[206:209], v[4:7]
	v_mfma_f32_16x16x32_bf16 v[0:3], v[244:247], v[206:209], v[0:3]
	s_setprio 0
	s_add_i32 s55, s55, 2
	s_add_u32 s6, s6, 0x100
	s_addc_u32 s7, s7, 0
	s_add_u32 s47, s47, 0x100
	s_addc_u32 s49, s49, 0
	s_cmp_gt_u32 s55, 13
	s_barrier
	s_cbranch_scc0 .LBB0_908
	s_lshl_b32 s2, s4, 8
	s_movk_i32 s3, 0x1600
	s_movk_i32 s84, 0x1600
	v_bfe_u32 v158, v231, 4, 1
	v_mul_u32_u24_e32 v158, 0x15ff8, v158
	v_lshl_or_b32 v159, s29, 7, v136
	v_lshl_add_u32 v194, v159, 1, v158
	v_mov_b32_e32 v195, 0
	v_add_u32_e32 v178, s2, v134
	v_mul_u32_u24_e32 v178, 0x1600, v178
	v_mov_b32_e32 v179, 0
	v_lshl_add_u64 v[178:179], s[44:45], 0, v[178:179]
	v_lshl_add_u64 v[178:179], v[178:179], 0, v[194:195]
	v_add_u32_e32 v180, s2, v138
	v_mul_u32_u24_e32 v180, 0x1600, v180
	v_mov_b32_e32 v181, 0
	v_lshl_add_u64 v[180:181], s[44:45], 0, v[180:181]
	v_lshl_add_u64 v[180:181], v[180:181], 0, v[194:195]
	v_add_u32_e32 v182, s2, v140
	v_mul_u32_u24_e32 v182, 0x1600, v182
	v_mov_b32_e32 v183, 0
	v_lshl_add_u64 v[182:183], s[44:45], 0, v[182:183]
	v_lshl_add_u64 v[182:183], v[182:183], 0, v[194:195]
	v_add_u32_e32 v184, s2, v142
	v_mul_u32_u24_e32 v184, 0x1600, v184
	v_mov_b32_e32 v185, 0
	v_lshl_add_u64 v[184:185], s[44:45], 0, v[184:185]
	v_lshl_add_u64 v[184:185], v[184:185], 0, v[194:195]
	s_and_b64 vcc, exec, s[40:41]
	s_mov_b32 s29, s46
	s_mov_b32 s4, s48
	s_mov_b64 s[8:9], s[52:53]
	s_mov_b64 s[6:7], s[50:51]
	v_mov_b32_e32 v158, 0xbfb8aa3b
	v_mov_b32_e32 v159, 0xbfb8aa3b
	v_pk_mul_f32 v[186:187], v[124:125], v[158:159]
	v_pk_mul_f32 v[188:189], v[126:127], v[158:159]
	v_pk_mul_f32 v[190:191], v[108:109], v[158:159]
	v_pk_mul_f32 v[192:193], v[110:111], v[158:159]
	v_exp_f32_e32 v186, v186
	v_exp_f32_e32 v187, v187
	v_exp_f32_e32 v188, v188
	v_exp_f32_e32 v189, v189
	v_exp_f32_e32 v190, v190
	v_exp_f32_e32 v191, v191
	v_exp_f32_e32 v192, v192
	v_exp_f32_e32 v193, v193
	v_pk_add_f32 v[186:187], v[186:187], 1.0 op_sel_hi:[1,0]
	v_pk_add_f32 v[188:189], v[188:189], 1.0 op_sel_hi:[1,0]
	v_pk_add_f32 v[190:191], v[190:191], 1.0 op_sel_hi:[1,0]
	v_pk_add_f32 v[192:193], v[192:193], 1.0 op_sel_hi:[1,0]
	v_rcp_f32_e32 v186, v186
	v_rcp_f32_e32 v187, v187
	v_rcp_f32_e32 v188, v188
	v_rcp_f32_e32 v189, v189
	v_rcp_f32_e32 v190, v190
	v_rcp_f32_e32 v191, v191
	v_rcp_f32_e32 v192, v192
	v_rcp_f32_e32 v193, v193
	v_pk_mul_f32 v[186:187], v[124:125], v[186:187]
	v_pk_mul_f32 v[188:189], v[126:127], v[188:189]
	v_pk_mul_f32 v[190:191], v[108:109], v[190:191]
	v_pk_mul_f32 v[192:193], v[110:111], v[192:193]
	v_pk_mul_f32 v[186:187], v[120:121], v[186:187]
	v_pk_mul_f32 v[188:189], v[122:123], v[188:189]
	v_pk_mul_f32 v[190:191], v[104:105], v[190:191]
	v_pk_mul_f32 v[192:193], v[106:107], v[192:193]
	v_cvt_pk_bf16_f32 v196, v186, v187
	v_cvt_pk_bf16_f32 v197, v188, v189
	v_cvt_pk_bf16_f32 v198, v190, v191
	v_cvt_pk_bf16_f32 v199, v192, v193
	s_nop 1
	v_permlane16_swap_b32_e32 v196, v198
	v_permlane16_swap_b32_e32 v197, v199
	global_store_dwordx4 v[178:179], v[196:199], off
	v_pk_mul_f32 v[186:187], v[116:117], v[158:159]
	v_pk_mul_f32 v[188:189], v[118:119], v[158:159]
; __device__ __forceinline__ uint32_t pack2(float a, float b) { uint32_t r; asm("v_cvt_pk_bf16_f32 %0, %1, %2" : "=v"(r) : "v"(a), "v"(b)); return r; }
; __device__ __forceinline__ float siluf_(float x) { return x * __builtin_amdgcn_rcpf(1.0f + __expf(-x)); }
;   __device__ __forceinline__ void operator()(const f32x4 (&acc)[2][2][4][2], const pg8::Unit& u, int wr, int wc, int fr, int fq) const {
;     ...
;         if (kind == EPI_SWIGLU) {
; #pragma unroll
;           for (int bj = 0; bj < 2; ++bj) {
;             int hc = u.pn * 128 + bj * 64 + wc * 16 + fq * 4;
;             f32x4 g = acc[ai][bj][m][0], up = acc[ai][bj][m][1];
;             uint2 o; o.x = pack2(siluf_(g[0]) * up[0], siluf_(g[1]) * up[1]); o.y = pack2(siluf_(g[2]) * up[2], siluf_(g[3]) * up[3]);
;             *(uint2*)(outb + (size_t)row * ldo + hc) = o;
;           }
	v_pk_mul_f32 v[190:191], v[100:101], v[158:159]
	v_pk_mul_f32 v[192:193], v[102:103], v[158:159]
	v_exp_f32_e32 v186, v186
	v_exp_f32_e32 v187, v187
	v_exp_f32_e32 v188, v188
	v_exp_f32_e32 v189, v189
	v_exp_f32_e32 v190, v190
	v_exp_f32_e32 v191, v191
	v_exp_f32_e32 v192, v192
	v_exp_f32_e32 v193, v193
	v_pk_add_f32 v[186:187], v[186:187], 1.0 op_sel_hi:[1,0]
	v_pk_add_f32 v[188:189], v[188:189], 1.0 op_sel_hi:[1,0]
	v_pk_add_f32 v[190:191], v[190:191], 1.0 op_sel_hi:[1,0]
	v_pk_add_f32 v[192:193], v[192:193], 1.0 op_sel_hi:[1,0]
	v_rcp_f32_e32 v186, v186
	v_rcp_f32_e32 v187, v187
	v_rcp_f32_e32 v188, v188
	v_rcp_f32_e32 v189, v189
	v_rcp_f32_e32 v190, v190
	v_rcp_f32_e32 v191, v191
	v_rcp_f32_e32 v192, v192
	v_rcp_f32_e32 v193, v193
	v_pk_mul_f32 v[186:187], v[116:117], v[186:187]
	v_pk_mul_f32 v[188:189], v[118:119], v[188:189]
	v_pk_mul_f32 v[190:191], v[100:101], v[190:191]
	v_pk_mul_f32 v[192:193], v[102:103], v[192:193]
	v_pk_mul_f32 v[186:187], v[112:113], v[186:187]
	v_pk_mul_f32 v[188:189], v[114:115], v[188:189]
	v_pk_mul_f32 v[190:191], v[96:97], v[190:191]
	v_pk_mul_f32 v[192:193], v[98:99], v[192:193]
	v_cvt_pk_bf16_f32 v200, v186, v187
	v_cvt_pk_bf16_f32 v201, v188, v189
	v_cvt_pk_bf16_f32 v202, v190, v191
	v_cvt_pk_bf16_f32 v203, v192, v193
	s_nop 1
	v_permlane16_swap_b32_e32 v200, v202
	v_permlane16_swap_b32_e32 v201, v203
	global_store_dwordx4 v[178:179], v[200:203], off offset:128
	v_pk_mul_f32 v[186:187], v[92:93], v[158:159]
	v_pk_mul_f32 v[188:189], v[94:95], v[158:159]
	v_pk_mul_f32 v[190:191], v[76:77], v[158:159]
	v_pk_mul_f32 v[192:193], v[78:79], v[158:159]
	v_exp_f32_e32 v186, v186
	v_exp_f32_e32 v187, v187
	v_exp_f32_e32 v188, v188
	v_exp_f32_e32 v189, v189
	v_exp_f32_e32 v190, v190
	v_exp_f32_e32 v191, v191
	v_exp_f32_e32 v192, v192
	v_exp_f32_e32 v193, v193
	v_pk_add_f32 v[186:187], v[186:187], 1.0 op_sel_hi:[1,0]
	v_pk_add_f32 v[188:189], v[188:189], 1.0 op_sel_hi:[1,0]
	v_pk_add_f32 v[190:191], v[190:191], 1.0 op_sel_hi:[1,0]
	v_pk_add_f32 v[192:193], v[192:193], 1.0 op_sel_hi:[1,0]
	v_rcp_f32_e32 v186, v186
	v_rcp_f32_e32 v187, v187
	v_rcp_f32_e32 v188, v188
	v_rcp_f32_e32 v189, v189
	v_rcp_f32_e32 v190, v190
	v_rcp_f32_e32 v191, v191
	v_rcp_f32_e32 v192, v192
	v_rcp_f32_e32 v193, v193
	v_pk_mul_f32 v[186:187], v[92:93], v[186:187]
	v_pk_mul_f32 v[188:189], v[94:95], v[188:189]
	v_pk_mul_f32 v[190:191], v[76:77], v[190:191]
	v_pk_mul_f32 v[192:193], v[78:79], v[192:193]
	v_pk_mul_f32 v[186:187], v[88:89], v[186:187]
	v_pk_mul_f32 v[188:189], v[90:91], v[188:189]
	v_pk_mul_f32 v[190:191], v[72:73], v[190:191]
	v_pk_mul_f32 v[192:193], v[74:75], v[192:193]
	v_cvt_pk_bf16_f32 v150, v186, v187
	v_cvt_pk_bf16_f32 v151, v188, v189
	v_cvt_pk_bf16_f32 v152, v190, v191
	v_cvt_pk_bf16_f32 v153, v192, v193
	s_nop 1
	v_permlane16_swap_b32_e32 v150, v152
	v_permlane16_swap_b32_e32 v151, v153
	global_store_dwordx4 v[180:181], v[150:153], off
	v_pk_mul_f32 v[186:187], v[84:85], v[158:159]
	v_pk_mul_f32 v[188:189], v[86:87], v[158:159]
	v_pk_mul_f32 v[190:191], v[68:69], v[158:159]
	v_pk_mul_f32 v[192:193], v[70:71], v[158:159]
	v_exp_f32_e32 v186, v186
	v_exp_f32_e32 v187, v187
	v_exp_f32_e32 v188, v188
	v_exp_f32_e32 v189, v189
	v_exp_f32_e32 v190, v190
	v_exp_f32_e32 v191, v191
	v_exp_f32_e32 v192, v192
	v_exp_f32_e32 v193, v193
	v_pk_add_f32 v[186:187], v[186:187], 1.0 op_sel_hi:[1,0]
	v_pk_add_f32 v[188:189], v[188:189], 1.0 op_sel_hi:[1,0]
	v_pk_add_f32 v[190:191], v[190:191], 1.0 op_sel_hi:[1,0]
	v_pk_add_f32 v[192:193], v[192:193], 1.0 op_sel_hi:[1,0]
	v_rcp_f32_e32 v186, v186
	v_rcp_f32_e32 v187, v187
	v_rcp_f32_e32 v188, v188
	v_rcp_f32_e32 v189, v189
	v_rcp_f32_e32 v190, v190
	v_rcp_f32_e32 v191, v191
	v_rcp_f32_e32 v192, v192
	v_rcp_f32_e32 v193, v193
	v_pk_mul_f32 v[186:187], v[84:85], v[186:187]
	v_pk_mul_f32 v[188:189], v[86:87], v[188:189]
	v_pk_mul_f32 v[190:191], v[68:69], v[190:191]
	v_pk_mul_f32 v[192:193], v[70:71], v[192:193]
	v_pk_mul_f32 v[186:187], v[80:81], v[186:187]
	v_pk_mul_f32 v[188:189], v[82:83], v[188:189]
	v_pk_mul_f32 v[190:191], v[64:65], v[190:191]
	v_pk_mul_f32 v[192:193], v[66:67], v[192:193]
	v_cvt_pk_bf16_f32 v154, v186, v187
	v_cvt_pk_bf16_f32 v155, v188, v189
	v_cvt_pk_bf16_f32 v156, v190, v191
	v_cvt_pk_bf16_f32 v157, v192, v193
	s_nop 1
	v_permlane16_swap_b32_e32 v154, v156
	v_permlane16_swap_b32_e32 v155, v157
	global_store_dwordx4 v[180:181], v[154:157], off offset:128
	v_pk_mul_f32 v[186:187], v[60:61], v[158:159]
	v_pk_mul_f32 v[188:189], v[62:63], v[158:159]
	v_pk_mul_f32 v[190:191], v[44:45], v[158:159]
	v_pk_mul_f32 v[192:193], v[46:47], v[158:159]
	v_exp_f32_e32 v186, v186
	v_exp_f32_e32 v187, v187
	v_exp_f32_e32 v188, v188
	v_exp_f32_e32 v189, v189
	v_exp_f32_e32 v190, v190
	v_exp_f32_e32 v191, v191
	v_exp_f32_e32 v192, v192
	v_exp_f32_e32 v193, v193
	v_pk_add_f32 v[186:187], v[186:187], 1.0 op_sel_hi:[1,0]
	v_pk_add_f32 v[188:189], v[188:189], 1.0 op_sel_hi:[1,0]
	v_pk_add_f32 v[190:191], v[190:191], 1.0 op_sel_hi:[1,0]
	v_pk_add_f32 v[192:193], v[192:193], 1.0 op_sel_hi:[1,0]
	v_rcp_f32_e32 v186, v186
	v_rcp_f32_e32 v187, v187
	v_rcp_f32_e32 v188, v188
	v_rcp_f32_e32 v189, v189
	v_rcp_f32_e32 v190, v190
	v_rcp_f32_e32 v191, v191
	v_rcp_f32_e32 v192, v192
	v_rcp_f32_e32 v193, v193
; __device__ __forceinline__ uint32_t pack2(float a, float b) { uint32_t r; asm("v_cvt_pk_bf16_f32 %0, %1, %2" : "=v"(r) : "v"(a), "v"(b)); return r; }
; __device__ __forceinline__ float siluf_(float x) { return x * __builtin_amdgcn_rcpf(1.0f + __expf(-x)); }
; #define PG8_WAIT_V(n) asm volatile("s_waitcnt vmcnt(" #n ")" ::: "memory")
; #define PG8_BAR __builtin_amdgcn_s_barrier()
; template <class Epi>
; __device__ __forceinline__ void gemm_phase(PG8_LAS unsigned char* lds, const Gemm g, const Sched& S, const Epi& E) {
;     ...
;     PG8_WAIT_V(0);
;     if (wr == 0) PG8_BAR;
;     PG8_BAR;
;   __device__ __forceinline__ void operator()(const f32x4 (&acc)[2][2][4][2], const pg8::Unit& u, int wr, int wc, int fr, int fq) const {
;     ...
;         if (kind == EPI_SWIGLU) {
; #pragma unroll
;           for (int bj = 0; bj < 2; ++bj) {
;             int hc = u.pn * 128 + bj * 64 + wc * 16 + fq * 4;
;             f32x4 g = acc[ai][bj][m][0], up = acc[ai][bj][m][1];
;             uint2 o; o.x = pack2(siluf_(g[0]) * up[0], siluf_(g[1]) * up[1]); o.y = pack2(siluf_(g[2]) * up[2], siluf_(g[3]) * up[3]);
;             *(uint2*)(outb + (size_t)row * ldo + hc) = o;
;           }
	v_pk_mul_f32 v[186:187], v[60:61], v[186:187]
	v_pk_mul_f32 v[188:189], v[62:63], v[188:189]
	v_pk_mul_f32 v[190:191], v[44:45], v[190:191]
	v_pk_mul_f32 v[192:193], v[46:47], v[192:193]
	v_pk_mul_f32 v[186:187], v[56:57], v[186:187]
	v_pk_mul_f32 v[188:189], v[58:59], v[188:189]
	v_pk_mul_f32 v[190:191], v[40:41], v[190:191]
	v_pk_mul_f32 v[192:193], v[42:43], v[192:193]
	v_cvt_pk_bf16_f32 v196, v186, v187
	v_cvt_pk_bf16_f32 v197, v188, v189
	v_cvt_pk_bf16_f32 v198, v190, v191
	v_cvt_pk_bf16_f32 v199, v192, v193
	s_nop 1
	v_permlane16_swap_b32_e32 v196, v198
	v_permlane16_swap_b32_e32 v197, v199
	global_store_dwordx4 v[182:183], v[196:199], off
	v_pk_mul_f32 v[186:187], v[52:53], v[158:159]
	v_pk_mul_f32 v[188:189], v[54:55], v[158:159]
	v_pk_mul_f32 v[190:191], v[36:37], v[158:159]
	v_pk_mul_f32 v[192:193], v[38:39], v[158:159]
	v_exp_f32_e32 v186, v186
	v_exp_f32_e32 v187, v187
	v_exp_f32_e32 v188, v188
	v_exp_f32_e32 v189, v189
	v_exp_f32_e32 v190, v190
	v_exp_f32_e32 v191, v191
	v_exp_f32_e32 v192, v192
	v_exp_f32_e32 v193, v193
	v_pk_add_f32 v[186:187], v[186:187], 1.0 op_sel_hi:[1,0]
	v_pk_add_f32 v[188:189], v[188:189], 1.0 op_sel_hi:[1,0]
	v_pk_add_f32 v[190:191], v[190:191], 1.0 op_sel_hi:[1,0]
	v_pk_add_f32 v[192:193], v[192:193], 1.0 op_sel_hi:[1,0]
	v_rcp_f32_e32 v186, v186
	v_rcp_f32_e32 v187, v187
	v_rcp_f32_e32 v188, v188
	v_rcp_f32_e32 v189, v189
	v_rcp_f32_e32 v190, v190
	v_rcp_f32_e32 v191, v191
	v_rcp_f32_e32 v192, v192
	v_rcp_f32_e32 v193, v193
	v_pk_mul_f32 v[186:187], v[52:53], v[186:187]
	v_pk_mul_f32 v[188:189], v[54:55], v[188:189]
	v_pk_mul_f32 v[190:191], v[36:37], v[190:191]
	v_pk_mul_f32 v[192:193], v[38:39], v[192:193]
	v_pk_mul_f32 v[186:187], v[48:49], v[186:187]
	v_pk_mul_f32 v[188:189], v[50:51], v[188:189]
	v_pk_mul_f32 v[190:191], v[32:33], v[190:191]
	v_pk_mul_f32 v[192:193], v[34:35], v[192:193]
	v_cvt_pk_bf16_f32 v200, v186, v187
	v_cvt_pk_bf16_f32 v201, v188, v189
	v_cvt_pk_bf16_f32 v202, v190, v191
	v_cvt_pk_bf16_f32 v203, v192, v193
	s_nop 1
	v_permlane16_swap_b32_e32 v200, v202
	v_permlane16_swap_b32_e32 v201, v203
	global_store_dwordx4 v[182:183], v[200:203], off offset:128
	v_pk_mul_f32 v[186:187], v[28:29], v[158:159]
	v_pk_mul_f32 v[188:189], v[30:31], v[158:159]
	v_pk_mul_f32 v[190:191], v[12:13], v[158:159]
	v_pk_mul_f32 v[192:193], v[14:15], v[158:159]
	v_exp_f32_e32 v186, v186
	v_exp_f32_e32 v187, v187
	v_exp_f32_e32 v188, v188
	v_exp_f32_e32 v189, v189
	v_exp_f32_e32 v190, v190
	v_exp_f32_e32 v191, v191
	v_exp_f32_e32 v192, v192
	v_exp_f32_e32 v193, v193
	v_pk_add_f32 v[186:187], v[186:187], 1.0 op_sel_hi:[1,0]
	v_pk_add_f32 v[188:189], v[188:189], 1.0 op_sel_hi:[1,0]
	v_pk_add_f32 v[190:191], v[190:191], 1.0 op_sel_hi:[1,0]
	v_pk_add_f32 v[192:193], v[192:193], 1.0 op_sel_hi:[1,0]
	v_rcp_f32_e32 v186, v186
	v_rcp_f32_e32 v187, v187
	v_rcp_f32_e32 v188, v188
	v_rcp_f32_e32 v189, v189
	v_rcp_f32_e32 v190, v190
	v_rcp_f32_e32 v191, v191
	v_rcp_f32_e32 v192, v192
	v_rcp_f32_e32 v193, v193
	v_pk_mul_f32 v[186:187], v[28:29], v[186:187]
	v_pk_mul_f32 v[188:189], v[30:31], v[188:189]
	v_pk_mul_f32 v[190:191], v[12:13], v[190:191]
	v_pk_mul_f32 v[192:193], v[14:15], v[192:193]
	v_pk_mul_f32 v[186:187], v[24:25], v[186:187]
	v_pk_mul_f32 v[188:189], v[26:27], v[188:189]
	v_pk_mul_f32 v[190:191], v[8:9], v[190:191]
	v_pk_mul_f32 v[192:193], v[10:11], v[192:193]
	v_cvt_pk_bf16_f32 v150, v186, v187
	v_cvt_pk_bf16_f32 v151, v188, v189
	v_cvt_pk_bf16_f32 v152, v190, v191
	v_cvt_pk_bf16_f32 v153, v192, v193
	s_nop 1
	v_permlane16_swap_b32_e32 v150, v152
	v_permlane16_swap_b32_e32 v151, v153
	global_store_dwordx4 v[184:185], v[150:153], off
	v_pk_mul_f32 v[186:187], v[20:21], v[158:159]
	v_pk_mul_f32 v[188:189], v[22:23], v[158:159]
	v_pk_mul_f32 v[190:191], v[4:5], v[158:159]
	v_pk_mul_f32 v[192:193], v[6:7], v[158:159]
	v_exp_f32_e32 v186, v186
	v_exp_f32_e32 v187, v187
	v_exp_f32_e32 v188, v188
	v_exp_f32_e32 v189, v189
	v_exp_f32_e32 v190, v190
	v_exp_f32_e32 v191, v191
	v_exp_f32_e32 v192, v192
	v_exp_f32_e32 v193, v193
	v_pk_add_f32 v[186:187], v[186:187], 1.0 op_sel_hi:[1,0]
	v_pk_add_f32 v[188:189], v[188:189], 1.0 op_sel_hi:[1,0]
	v_pk_add_f32 v[190:191], v[190:191], 1.0 op_sel_hi:[1,0]
	v_pk_add_f32 v[192:193], v[192:193], 1.0 op_sel_hi:[1,0]
	v_rcp_f32_e32 v186, v186
	v_rcp_f32_e32 v187, v187
	v_rcp_f32_e32 v188, v188
	v_rcp_f32_e32 v189, v189
	v_rcp_f32_e32 v190, v190
	v_rcp_f32_e32 v191, v191
	v_rcp_f32_e32 v192, v192
	v_rcp_f32_e32 v193, v193
	v_pk_mul_f32 v[186:187], v[20:21], v[186:187]
	v_pk_mul_f32 v[188:189], v[22:23], v[188:189]
	v_pk_mul_f32 v[190:191], v[4:5], v[190:191]
	v_pk_mul_f32 v[192:193], v[6:7], v[192:193]
	v_pk_mul_f32 v[186:187], v[16:17], v[186:187]
	v_pk_mul_f32 v[188:189], v[18:19], v[188:189]
	v_pk_mul_f32 v[190:191], v[0:1], v[190:191]
	v_pk_mul_f32 v[192:193], v[2:3], v[192:193]
	v_cvt_pk_bf16_f32 v154, v186, v187
	v_cvt_pk_bf16_f32 v155, v188, v189
	v_cvt_pk_bf16_f32 v156, v190, v191
	v_cvt_pk_bf16_f32 v157, v192, v193
	s_nop 1
	v_permlane16_swap_b32_e32 v154, v156
	v_permlane16_swap_b32_e32 v155, v157
	global_store_dwordx4 v[184:185], v[154:157], off offset:128
	s_cbranch_vccz .LBB0_901
	s_waitcnt vmcnt(0)
	s_cmpk_gt_u32 s15, 0xff
	s_cbranch_scc1 .LBB0_912
	s_barrier
